# v58 + attention softmax row-sum chains: exact-identity VALU removed (x+0.0 adds, zero-init + first add folded), 38 instructions fewer in the VALU-bound step
# speedup vs baseline: 1.0161x; 1.0161x over previous
.LBB0_1602:
	v_lshlrev_b32_e32 v34, 1, v0
	v_lshlrev_b32_e32 v0, 4, v0
	v_and_b32_e32 v237, 32, v34
	v_and_b32_e32 v0, 0xc0, v0
	v_lshl_or_b32 v236, v231, 8, v0
	v_add_u32_e32 v0, 0, v237
	v_add3_u32 v244, v0, v235, v236
	v_max3_f32 v0, v18, v19, v2
	v_max3_f32 v34, v20, v21, v3
	s_and_b32 s11, s0, 0x3fffffc0
	v_max3_f32 v0, v0, v4, v5
	v_max3_f32 v34, v34, v24, v25
	s_lshl_b32 s11, s11, 2
	v_max3_f32 v0, v0, v22, v23
	v_max3_f32 v34, v34, v8, v9
	s_add_i32 s22, s27, 0x100
	v_max3_f32 v0, v0, v6, v7
	v_max3_f32 v34, v34, v28, v29
	s_add_i32 s56, s11, 0
	v_max3_f32 v0, v0, v26, v27
	v_max3_f32 v34, v34, v12, v13
	s_add_i32 s56, s56, 0x12000
	v_max3_f32 v0, v0, v10, v11
	v_max3_f32 v34, v34, v32, v33
	s_lshr_b32 s60, s22, 6
	v_max3_f32 v0, v0, v30, v31
	v_max3_f32 v34, v34, v16, v17
	s_add_u32 s22, s16, 0x60000
	v_max3_f32 v0, v0, v14, v15
	s_waitcnt vmcnt(0) lgkmcnt(0)
	s_barrier
	s_addc_u32 s23, s17, 0
	v_max_f32_e32 v0, v0, v34
	s_mov_b32 s11, m0
	s_mov_b32 m0, s57
	s_nop 0
	global_load_lds_dwordx4 v241, s[22:23]
	s_mov_b32 m0, s11
	s_add_u32 s22, s18, 0x20000
	v_mov_b32_e32 v34, v0
	s_nop 1
	v_permlane32_swap_b32_e32 v0, v34
	v_max_f32_e32 v0, v0, v34
	s_addc_u32 s23, s19, 0
	v_sub_f32_e32 v18, v18, v0
	v_sub_f32_e32 v19, v19, v0
	v_sub_f32_e32 v20, v20, v0
	v_add_f32_e32 v228, v1, v0
	v_sub_f32_e32 v2, v2, v0
	v_sub_f32_e32 v3, v3, v0
	s_nop 0
	v_exp_f32_e32 v96, v18
	v_exp_f32_e32 v97, v19
	v_exp_f32_e32 v98, v20
	v_sub_f32_e32 v4, v4, v0
	v_sub_f32_e32 v21, v21, v0
	v_sub_f32_e32 v5, v5, v0
	v_sub_f32_e32 v22, v22, v0
	v_sub_f32_e32 v6, v6, v0
	v_sub_f32_e32 v23, v23, v0
	v_sub_f32_e32 v7, v7, v0
	v_sub_f32_e32 v24, v24, v0
	v_sub_f32_e32 v8, v8, v0
	v_sub_f32_e32 v25, v25, v0
	v_sub_f32_e32 v9, v9, v0
	v_sub_f32_e32 v26, v26, v0
	v_sub_f32_e32 v10, v10, v0
	v_sub_f32_e32 v27, v27, v0
	v_sub_f32_e32 v11, v11, v0
	v_sub_f32_e32 v28, v28, v0
	v_sub_f32_e32 v12, v12, v0
	v_sub_f32_e32 v29, v29, v0
	v_sub_f32_e32 v13, v13, v0
	v_sub_f32_e32 v30, v30, v0
	v_sub_f32_e32 v14, v14, v0
	v_sub_f32_e32 v31, v31, v0
	v_sub_f32_e32 v15, v15, v0
	v_sub_f32_e32 v32, v32, v0
	v_sub_f32_e32 v16, v16, v0
	v_sub_f32_e32 v33, v33, v0
	v_sub_f32_e32 v0, v17, v0
	s_nop 0
	v_exp_f32_e32 v99, v21
	v_exp_f32_e32 v100, v22
	v_exp_f32_e32 v95, v0
	v_exp_f32_e32 v101, v23
	v_add_f32_e32 v0, v96, v97
	v_exp_f32_e32 v102, v24
	v_add_f32_e32 v0, v0, v98
	v_exp_f32_e32 v103, v25
	v_add_f32_e32 v0, v0, v99
	v_exp_f32_e32 v104, v26
	v_add_f32_e32 v0, v0, v100
	v_exp_f32_e32 v105, v27
	v_add_f32_e32 v0, v0, v101
	v_exp_f32_e32 v106, v28
	v_add_f32_e32 v0, v0, v102
	v_exp_f32_e32 v107, v29
	v_add_f32_e32 v0, v0, v103
	s_cmp_lg_u32 0, -1
	v_exp_f32_e32 v108, v30
	v_add_f32_e32 v0, v0, v104
	s_cselect_b32 s11, 0, 0
	v_exp_f32_e32 v109, v31
	v_add_f32_e32 v0, v0, v105
	s_add_i32 s24, s11, s10
	v_exp_f32_e32 v110, v32
	v_add_f32_e32 v0, v0, v106
	s_add_i32 s10, s24, 0x8000
	v_exp_f32_e32 v111, v33
	v_add_f32_e32 v0, v0, v107
	s_mov_b32 s11, m0
	s_mov_b32 m0, s10
	s_nop 0
	global_load_lds_dwordx4 v242, s[22:23]
	s_mov_b32 m0, s11
	s_add_u32 s10, s18, 0x20080
	v_exp_f32_e32 v80, v2
	v_add_f32_e32 v0, v0, v108
	s_addc_u32 s11, s19, 0
	s_add_i32 s24, s24, 0xe000
	s_mov_b32 s22, m0
	s_mov_b32 m0, s24
	s_nop 0
	global_load_lds_dwordx4 v242, s[10:11]
	s_mov_b32 m0, s22
	v_exp_f32_e32 v81, v3
	v_add_f32_e32 v0, v0, v109
	ds_read_b128 v[204:207], v243 offset:8192
	ds_read_b128 v[200:203], v243 offset:8704
	ds_read_b128 v[196:199], v243 offset:10240
	ds_read_b128 v[192:195], v243 offset:10752
	ds_read_b128 v[188:191], v243 offset:12288
	ds_read_b128 v[184:187], v243 offset:12800
	ds_read_b128 v[180:183], v243 offset:14336
	ds_read_b128 v[176:179], v243 offset:14848
	v_exp_f32_e32 v82, v4
	v_add_f32_e32 v0, v0, v110
	v_exp_f32_e32 v83, v5
	v_add_f32_e32 v0, v0, v111
	v_exp_f32_e32 v84, v6
	v_add_f32_e32 v0, v80, v0
	v_exp_f32_e32 v85, v7
	v_add_f32_e32 v0, v81, v0
	v_exp_f32_e32 v86, v8
	v_add_f32_e32 v0, v82, v0
	v_add_f32_e32 v0, v83, v0
	v_exp_f32_e32 v87, v9
	v_exp_f32_e32 v88, v10
	v_exp_f32_e32 v89, v11
	v_exp_f32_e32 v90, v12
	v_exp_f32_e32 v91, v13
	v_exp_f32_e32 v92, v14
	v_exp_f32_e32 v93, v15
	v_exp_f32_e32 v94, v16
	v_add_f32_e32 v0, v84, v0
	v_add_f32_e32 v0, v85, v0
	s_waitcnt vmcnt(3) lgkmcnt(0)
	s_barrier
	v_add_f32_e32 v0, v86, v0
	s_mov_b32 s0, 1
	s_mov_b32 s28, 0
	v_add_f32_e32 v224, 0, v0
	s_andn2_b64 vcc, exec, s[8:9]
	v_cmp_gt_u32_e64 s[8:9], 32, v232
	v_lshlrev_b32_e32 v245, 4, v231
	v_lshl_add_u32 v238, v233, 2, s56
	v_mov_b32_e32 v0, v1
	v_mov_b32_e32 v2, v1
	v_mov_b32_e32 v3, v1
	v_mov_b32_e32 v4, v1
	v_mov_b32_e32 v5, v1
	v_mov_b32_e32 v6, v1
	v_mov_b32_e32 v7, v1
	v_mov_b32_e32 v8, v1
	v_mov_b32_e32 v9, v1
	v_mov_b32_e32 v10, v1
	v_mov_b32_e32 v11, v1
	v_mov_b32_e32 v12, v1
	v_mov_b32_e32 v13, v1
	v_mov_b32_e32 v14, v1
	v_mov_b32_e32 v15, v1
	s_cbranch_vccnz .LBB0_1618
	v_mov_b64_e32 v[78:79], v[14:15]
	v_mov_b64_e32 v[62:63], v[14:15]
	v_mov_b64_e32 v[46:47], v[14:15]
	v_mov_b64_e32 v[30:31], v[14:15]
	s_movk_i32 s28, 0x4000
	s_movk_i32 s29, 0x2000
	s_mov_b32 s22, 0
	s_mov_b32 s0, 6
	s_mov_b64 s[10:11], 0
	v_mov_b64_e32 v[76:77], v[12:13]
	v_mov_b64_e32 v[74:75], v[10:11]
	v_mov_b64_e32 v[72:73], v[8:9]
	v_mov_b64_e32 v[70:71], v[6:7]
	v_mov_b64_e32 v[68:69], v[4:5]
	v_mov_b64_e32 v[66:67], v[2:3]
	v_mov_b64_e32 v[64:65], v[0:1]
	v_mov_b64_e32 v[60:61], v[12:13]
	v_mov_b64_e32 v[58:59], v[10:11]
	v_mov_b64_e32 v[56:57], v[8:9]
	v_mov_b64_e32 v[54:55], v[6:7]
	v_mov_b64_e32 v[52:53], v[4:5]
	v_mov_b64_e32 v[50:51], v[2:3]
	v_mov_b64_e32 v[48:49], v[0:1]
	v_mov_b64_e32 v[44:45], v[12:13]
	v_mov_b64_e32 v[42:43], v[10:11]
	v_mov_b64_e32 v[40:41], v[8:9]
	v_mov_b64_e32 v[38:39], v[6:7]
	v_mov_b64_e32 v[36:37], v[4:5]
	v_mov_b64_e32 v[34:35], v[2:3]
	v_mov_b64_e32 v[32:33], v[0:1]
	v_mov_b64_e32 v[28:29], v[12:13]
	v_mov_b64_e32 v[26:27], v[10:11]
	v_mov_b64_e32 v[24:25], v[8:9]
	v_mov_b64_e32 v[22:23], v[6:7]
	v_mov_b64_e32 v[20:21], v[4:5]
	v_mov_b64_e32 v[18:19], v[2:3]
	v_mov_b64_e32 v[16:17], v[0:1]

.LBB0_1605:
	s_waitcnt lgkmcnt(14)
	v_mfma_f32_32x32x16_bf16 v[64:79], v[156:159], v[208:211], v[64:79]
	v_exp_f32_e32 v96, v80
	v_exp_f32_e32 v97, v81
	ds_read_b64_tr_b16 v[118:119], v0 offset:49152
	ds_read_b64_tr_b16 v[120:121], v0 offset:49664
	s_waitcnt lgkmcnt(14)
	v_mfma_f32_32x32x16_bf16 v[48:63], v[156:159], v[204:207], v[48:63]
	v_exp_f32_e32 v98, v98
	v_exp_f32_e32 v99, v99
	ds_read_b64_tr_b16 v[122:123], v0 offset:53248
	ds_read_b64_tr_b16 v[124:125], v0 offset:53760
	v_add_u32_e32 v81, s28, v243
	ds_read_b128 v[112:115], v81
	ds_read_b128 v[128:131], v81 offset:512
	s_waitcnt lgkmcnt(14)
	v_mfma_f32_32x32x16_bf16 v[64:79], v[152:155], v[10:13], v[64:79]
	v_add_f32_e32 v80, v96, v97
	v_exp_f32_e32 v100, v100
	v_exp_f32_e32 v101, v101
	ds_read_b64_tr_b16 v[132:133], v0 offset:50176
	ds_read_b64_tr_b16 v[134:135], v0 offset:50688
	ds_read_b128 v[184:187], v81 offset:2048
	ds_read_b128 v[176:179], v81 offset:2560
	v_mfma_f32_32x32x16_bf16 v[48:63], v[152:155], v[6:9], v[48:63]
	v_add_f32_e32 v10, v80, v98
	v_exp_f32_e32 v102, v102
	v_exp_f32_e32 v103, v103
	ds_read_b64_tr_b16 v[136:137], v0 offset:54272
	ds_read_b64_tr_b16 v[138:139], v0 offset:54784
	ds_read_b128 v[180:183], v81 offset:4096
	ds_read_b128 v[6:9], v81 offset:4608
	s_waitcnt lgkmcnt(14)
	v_mfma_f32_32x32x16_bf16 v[64:79], v[148:151], v[2:5], v[64:79]
	v_add_f32_e32 v10, v10, v99
	v_exp_f32_e32 v104, v104
	v_exp_f32_e32 v105, v105
	v_add_f32_e32 v80, 0, v10
	ds_read_b64_tr_b16 v[140:141], v0 offset:51200
	ds_read_b64_tr_b16 v[142:143], v0 offset:51712
	ds_read_b128 v[10:13], v81 offset:6144
	ds_read_b128 v[2:5], v81 offset:6656
	v_mfma_f32_32x32x16_bf16 v[48:63], v[148:151], v[196:199], v[48:63]
	v_add_f32_e32 v80, v80, v100
	v_exp_f32_e32 v106, v106
	v_exp_f32_e32 v107, v107
	ds_read_b64_tr_b16 v[196:197], v0 offset:55296
	ds_read_b64_tr_b16 v[198:199], v0 offset:55808
	v_mfma_f32_32x32x16_bf16 v[64:79], v[144:147], v[192:195], v[64:79]
	v_add_f32_e32 v80, v80, v101
	v_exp_f32_e32 v108, v108
	v_exp_f32_e32 v109, v109
	ds_read_b64_tr_b16 v[192:193], v0 offset:52224
	ds_read_b64_tr_b16 v[194:195], v0 offset:52736
	v_mfma_f32_32x32x16_bf16 v[48:63], v[144:147], v[188:191], v[48:63]
	v_add_f32_e32 v80, v80, v102
	v_exp_f32_e32 v110, v110
	v_exp_f32_e32 v111, v111
	v_add_f32_e32 v117, 0, v80
	ds_read_b64_tr_b16 v[188:189], v0 offset:56320
	ds_read_b64_tr_b16 v[190:191], v0 offset:56832
	s_waitcnt lgkmcnt(14)
	v_mfma_f32_32x32x16_bf16 v[32:47], v[156:159], v[118:121], v[32:47]
	v_add_f32_e32 v0, v117, v103
	v_exp_f32_e32 v80, v14
	v_exp_f32_e32 v81, v15
	v_add_f32_e32 v0, v104, v0
	v_mfma_f32_32x32x16_bf16 v[16:31], v[156:159], v[122:125], v[16:31]
	v_add_f32_e32 v0, v105, v0
	v_exp_f32_e32 v82, v82
	v_exp_f32_e32 v83, v83
	v_add_f32_e32 v0, v106, v0
	v_mfma_f32_32x32x16_bf16 v[32:47], v[152:155], v[132:135], v[32:47]
	v_add_f32_e32 v0, v107, v0
	v_exp_f32_e32 v84, v84
	v_exp_f32_e32 v85, v85
	v_add_f32_e32 v0, v108, v0
	s_waitcnt lgkmcnt(12)
	v_mfma_f32_32x32x16_bf16 v[16:31], v[152:155], v[136:139], v[16:31]
	v_add_f32_e32 v0, v109, v0
	v_exp_f32_e32 v86, v86
	v_exp_f32_e32 v87, v87
	v_add_f32_e32 v0, v110, v0
	s_waitcnt lgkmcnt(8)
	v_mfma_f32_32x32x16_bf16 v[32:47], v[148:151], v[140:143], v[32:47]
	v_add_f32_e32 v0, v111, v0
	v_exp_f32_e32 v88, v88
	v_exp_f32_e32 v89, v89
	v_add_f32_e32 v0, v0, v80
	s_waitcnt lgkmcnt(4)
	v_mfma_f32_32x32x16_bf16 v[16:31], v[148:151], v[196:199], v[16:31]
	v_add_f32_e32 v0, v0, v81
	v_exp_f32_e32 v90, v90
	v_exp_f32_e32 v91, v91
	v_add_f32_e32 v0, v82, v0
	s_waitcnt lgkmcnt(2)
	v_mfma_f32_32x32x16_bf16 v[32:47], v[144:147], v[192:195], v[32:47]
	v_add_f32_e32 v0, v0, v83
	v_exp_f32_e32 v92, v92
	v_exp_f32_e32 v93, v93
	v_add_f32_e32 v0, v84, v0
	s_waitcnt lgkmcnt(0)
	v_mfma_f32_32x32x16_bf16 v[16:31], v[144:147], v[188:191], v[16:31]
	v_add_f32_e32 v0, v0, v85
	v_exp_f32_e32 v94, v94
	v_exp_f32_e32 v95, v95
	v_add_f32_e32 v14, v86, v0
	s_waitcnt vmcnt(3) lgkmcnt(0)
	s_barrier
	s_andn2_b64 vcc, exec, s[22:23]
	v_add_u32_e32 v0, s56, v245
	s_cbranch_vccnz .LBB0_1607
	s_waitcnt lgkmcnt(0)
	ds_read_b128 v[118:121], v0 offset:96
	ds_read_b128 v[122:125], v0 offset:64
	ds_read_b128 v[132:135], v0 offset:32
	ds_read_b128 v[136:139], v0
	s_waitcnt lgkmcnt(3)
	v_pk_mul_f32 v[76:77], v[76:77], v[118:119]
	s_waitcnt lgkmcnt(2)
	v_pk_mul_f32 v[72:73], v[72:73], v[122:123]
	s_waitcnt lgkmcnt(1)
	v_pk_mul_f32 v[68:69], v[68:69], v[132:133]
	v_pk_mul_f32 v[78:79], v[78:79], v[120:121]
	v_pk_mul_f32 v[74:75], v[74:75], v[124:125]
	v_pk_mul_f32 v[70:71], v[70:71], v[134:135]
	s_waitcnt lgkmcnt(0)
	v_pk_mul_f32 v[66:67], v[66:67], v[138:139]
	v_pk_mul_f32 v[64:65], v[64:65], v[136:137]
	v_pk_mul_f32 v[60:61], v[60:61], v[118:119]
	v_pk_mul_f32 v[56:57], v[56:57], v[122:123]
	v_pk_mul_f32 v[52:53], v[52:53], v[132:133]
	v_pk_mul_f32 v[62:63], v[62:63], v[120:121]
	v_pk_mul_f32 v[58:59], v[58:59], v[124:125]
	v_pk_mul_f32 v[54:55], v[54:55], v[134:135]
	v_pk_mul_f32 v[50:51], v[50:51], v[138:139]
	v_pk_mul_f32 v[48:49], v[48:49], v[136:137]
	v_pk_mul_f32 v[44:45], v[44:45], v[118:119]
	v_pk_mul_f32 v[40:41], v[40:41], v[122:123]
	v_pk_mul_f32 v[36:37], v[36:37], v[132:133]
	v_pk_mul_f32 v[46:47], v[46:47], v[120:121]
	v_pk_mul_f32 v[42:43], v[42:43], v[124:125]
	v_pk_mul_f32 v[38:39], v[38:39], v[134:135]
	v_pk_mul_f32 v[34:35], v[34:35], v[138:139]
	v_pk_mul_f32 v[32:33], v[32:33], v[136:137]
	v_pk_mul_f32 v[28:29], v[28:29], v[118:119]
	v_pk_mul_f32 v[24:25], v[24:25], v[122:123]
	v_pk_mul_f32 v[20:21], v[20:21], v[132:133]
	v_pk_mul_f32 v[30:31], v[30:31], v[120:121]
	v_pk_mul_f32 v[26:27], v[26:27], v[124:125]
	v_pk_mul_f32 v[22:23], v[22:23], v[134:135]
	v_pk_mul_f32 v[18:19], v[18:19], v[138:139]
	v_pk_mul_f32 v[16:17], v[16:17], v[136:137]

.LBB0_1608:
	s_waitcnt lgkmcnt(14)
	v_mfma_f32_32x32x16_bf16 v[64:79], v[156:159], v[196:199], v[64:79]
	v_exp_f32_e32 v96, v4
	v_exp_f32_e32 v97, v5
	ds_read_b64_tr_b16 v[112:113], v14 offset:49152
	ds_read_b64_tr_b16 v[114:115], v14 offset:49664
	s_waitcnt lgkmcnt(14)
	v_mfma_f32_32x32x16_bf16 v[48:63], v[156:159], v[192:195], v[48:63]
	v_exp_f32_e32 v98, v98
	v_exp_f32_e32 v99, v99
	ds_read_b64_tr_b16 v[116:117], v14 offset:53248
	ds_read_b64_tr_b16 v[118:119], v14 offset:53760
	v_add_u32_e32 v5, s61, v243
	ds_read_b128 v[204:207], v5
	ds_read_b128 v[200:203], v5 offset:512
	s_waitcnt lgkmcnt(14)
	v_mfma_f32_32x32x16_bf16 v[64:79], v[152:155], v[188:191], v[64:79]
	v_add_f32_e32 v4, v96, v97
	v_exp_f32_e32 v100, v100
	v_exp_f32_e32 v101, v101
	ds_read_b64_tr_b16 v[120:121], v14 offset:50176
	ds_read_b64_tr_b16 v[122:123], v14 offset:50688
	ds_read_b128 v[196:199], v5 offset:2048
	ds_read_b128 v[192:195], v5 offset:2560
	v_mfma_f32_32x32x16_bf16 v[48:63], v[152:155], v[184:187], v[48:63]
	v_add_f32_e32 v4, v4, v98
	v_exp_f32_e32 v102, v102
	v_exp_f32_e32 v103, v103
	ds_read_b64_tr_b16 v[124:125], v14 offset:54272
	ds_read_b64_tr_b16 v[126:127], v14 offset:54784
	ds_read_b128 v[188:191], v5 offset:4096
	ds_read_b128 v[184:187], v5 offset:4608
	s_waitcnt lgkmcnt(14)
	v_mfma_f32_32x32x16_bf16 v[64:79], v[148:151], v[176:179], v[64:79]
	v_add_f32_e32 v4, v4, v99
	v_exp_f32_e32 v104, v104
	v_exp_f32_e32 v105, v105
	ds_read_b64_tr_b16 v[128:129], v14 offset:51200
	ds_read_b64_tr_b16 v[130:131], v14 offset:51712
	ds_read_b128 v[180:183], v5 offset:6144
	ds_read_b128 v[176:179], v5 offset:6656
	v_mfma_f32_32x32x16_bf16 v[48:63], v[148:151], v[212:215], v[48:63]
	v_add_f32_e32 v4, v4, v100
	v_exp_f32_e32 v106, v106
	v_exp_f32_e32 v107, v107
	ds_read_b64_tr_b16 v[132:133], v14 offset:55296
	ds_read_b64_tr_b16 v[134:135], v14 offset:55808
	v_mfma_f32_32x32x16_bf16 v[64:79], v[144:147], v[208:211], v[64:79]
	v_add_f32_e32 v4, v4, v101
	v_exp_f32_e32 v108, v108
	v_exp_f32_e32 v109, v109
	ds_read_b64_tr_b16 v[136:137], v14 offset:52224
	ds_read_b64_tr_b16 v[138:139], v14 offset:52736
	v_mfma_f32_32x32x16_bf16 v[48:63], v[144:147], v[6:9], v[48:63]
	v_add_f32_e32 v4, v4, v102
	v_exp_f32_e32 v110, v110
	v_exp_f32_e32 v111, v111
	v_add_f32_e32 v11, 0, v4
	ds_read_b64_tr_b16 v[4:5], v14 offset:56320
	ds_read_b64_tr_b16 v[6:7], v14 offset:56832
	s_waitcnt lgkmcnt(14)
	v_mfma_f32_32x32x16_bf16 v[32:47], v[156:159], v[112:115], v[32:47]
	v_exp_f32_e32 v80, v2
	v_add_f32_e32 v2, v11, v103
	v_exp_f32_e32 v81, v3
	v_add_f32_e32 v2, v104, v2
	v_mfma_f32_32x32x16_bf16 v[16:31], v[156:159], v[116:119], v[16:31]
	v_add_f32_e32 v2, v105, v2
	v_exp_f32_e32 v82, v82
	v_exp_f32_e32 v83, v83
	v_add_f32_e32 v2, v106, v2
	v_mfma_f32_32x32x16_bf16 v[32:47], v[152:155], v[120:123], v[32:47]
	v_add_f32_e32 v2, v107, v2
	v_exp_f32_e32 v84, v84
	v_exp_f32_e32 v85, v85
	v_add_f32_e32 v2, v108, v2
	s_waitcnt lgkmcnt(12)
	v_mfma_f32_32x32x16_bf16 v[16:31], v[152:155], v[124:127], v[16:31]
	v_add_f32_e32 v2, v109, v2
	v_exp_f32_e32 v86, v86
	v_exp_f32_e32 v87, v87
	v_add_f32_e32 v2, v110, v2
	s_waitcnt lgkmcnt(8)
	v_mfma_f32_32x32x16_bf16 v[32:47], v[148:151], v[128:131], v[32:47]
	v_add_f32_e32 v2, v111, v2
	v_exp_f32_e32 v88, v88
	v_exp_f32_e32 v89, v89
	v_add_f32_e32 v2, v2, v80
	s_waitcnt lgkmcnt(4)
	v_mfma_f32_32x32x16_bf16 v[16:31], v[148:151], v[132:135], v[16:31]
	v_add_f32_e32 v2, v2, v81
	v_exp_f32_e32 v90, v90
	v_exp_f32_e32 v91, v91
	v_add_f32_e32 v2, v82, v2
	s_waitcnt lgkmcnt(2)
	v_mfma_f32_32x32x16_bf16 v[32:47], v[144:147], v[136:139], v[32:47]
	v_add_f32_e32 v2, v2, v83
	v_exp_f32_e32 v92, v92
	v_exp_f32_e32 v93, v93
	v_add_f32_e32 v2, v84, v2
	s_waitcnt lgkmcnt(0)
	v_mfma_f32_32x32x16_bf16 v[16:31], v[144:147], v[4:7], v[16:31]
	v_add_f32_e32 v2, v2, v85
	v_exp_f32_e32 v94, v94
	v_exp_f32_e32 v95, v95
	v_add_f32_e32 v2, v86, v2
	s_waitcnt vmcnt(3) lgkmcnt(0)
	s_barrier
	s_andn2_b64 vcc, exec, s[22:23]
	s_cbranch_vccnz .LBB0_1610
	s_waitcnt lgkmcnt(0)
	ds_read_b128 v[4:7], v0 offset:96
	ds_read_b128 v[12:15], v0 offset:64
	ds_read_b128 v[112:115], v0 offset:32
	ds_read_b128 v[116:119], v0
	s_waitcnt lgkmcnt(3)
	v_pk_mul_f32 v[76:77], v[76:77], v[4:5]
	s_waitcnt lgkmcnt(2)
	v_pk_mul_f32 v[72:73], v[72:73], v[12:13]
	s_waitcnt lgkmcnt(1)
	v_pk_mul_f32 v[68:69], v[68:69], v[112:113]
	v_pk_mul_f32 v[78:79], v[78:79], v[6:7]
	v_pk_mul_f32 v[74:75], v[74:75], v[14:15]
	v_pk_mul_f32 v[70:71], v[70:71], v[114:115]
	s_waitcnt lgkmcnt(0)
	v_pk_mul_f32 v[66:67], v[66:67], v[118:119]
	v_pk_mul_f32 v[64:65], v[64:65], v[116:117]
	v_pk_mul_f32 v[60:61], v[60:61], v[4:5]
	v_pk_mul_f32 v[56:57], v[56:57], v[12:13]
	v_pk_mul_f32 v[52:53], v[52:53], v[112:113]
	v_pk_mul_f32 v[62:63], v[62:63], v[6:7]
	v_pk_mul_f32 v[58:59], v[58:59], v[14:15]
	v_pk_mul_f32 v[54:55], v[54:55], v[114:115]
	v_pk_mul_f32 v[50:51], v[50:51], v[118:119]
	v_pk_mul_f32 v[48:49], v[48:49], v[116:117]
	v_pk_mul_f32 v[44:45], v[44:45], v[4:5]
	v_pk_mul_f32 v[40:41], v[40:41], v[12:13]
	v_pk_mul_f32 v[36:37], v[36:37], v[112:113]
	v_pk_mul_f32 v[46:47], v[46:47], v[6:7]
	v_pk_mul_f32 v[42:43], v[42:43], v[14:15]
	v_pk_mul_f32 v[38:39], v[38:39], v[114:115]
	v_pk_mul_f32 v[34:35], v[34:35], v[118:119]
	v_pk_mul_f32 v[32:33], v[32:33], v[116:117]
	v_pk_mul_f32 v[28:29], v[28:29], v[4:5]
	v_pk_mul_f32 v[24:25], v[24:25], v[12:13]
	v_pk_mul_f32 v[20:21], v[20:21], v[112:113]
	v_pk_mul_f32 v[30:31], v[30:31], v[6:7]
	v_pk_mul_f32 v[26:27], v[26:27], v[14:15]
	v_pk_mul_f32 v[22:23], v[22:23], v[114:115]
	v_pk_mul_f32 v[18:19], v[18:19], v[118:119]
	v_pk_mul_f32 v[16:17], v[16:17], v[116:117]

.LBB0_1621:
	s_waitcnt lgkmcnt(14)
	v_mfma_f32_32x32x16_bf16 v[64:79], v[156:159], v[208:211], v[64:79]
	v_exp_f32_e32 v96, v80
	v_exp_f32_e32 v97, v81
	ds_read_b64_tr_b16 v[112:113], v212 offset:49152
	ds_read_b64_tr_b16 v[114:115], v212 offset:49664
	s_waitcnt lgkmcnt(14)
	v_mfma_f32_32x32x16_bf16 v[48:63], v[156:159], v[204:207], v[48:63]
	v_exp_f32_e32 v98, v98
	v_exp_f32_e32 v99, v99
	ds_read_b64_tr_b16 v[116:117], v212 offset:53248
	ds_read_b64_tr_b16 v[118:119], v212 offset:53760
	s_waitcnt lgkmcnt(14)
	v_mfma_f32_32x32x16_bf16 v[64:79], v[152:155], v[200:203], v[64:79]
	v_add_f32_e32 v80, v96, v97
	v_exp_f32_e32 v100, v100
	v_exp_f32_e32 v101, v101
	ds_read_b64_tr_b16 v[120:121], v212 offset:50176
	ds_read_b64_tr_b16 v[122:123], v212 offset:50688
	s_waitcnt lgkmcnt(14)
	v_mfma_f32_32x32x16_bf16 v[48:63], v[152:155], v[172:175], v[48:63]
	v_add_f32_e32 v80, v80, v98
	v_exp_f32_e32 v102, v102
	v_exp_f32_e32 v103, v103
	ds_read_b64_tr_b16 v[124:125], v212 offset:54272
	ds_read_b64_tr_b16 v[126:127], v212 offset:54784
	s_waitcnt lgkmcnt(14)
	v_mfma_f32_32x32x16_bf16 v[64:79], v[148:151], v[168:171], v[64:79]
	v_add_f32_e32 v80, v80, v99
	v_exp_f32_e32 v104, v104
	v_exp_f32_e32 v105, v105
	ds_read_b64_tr_b16 v[128:129], v212 offset:51200
	ds_read_b64_tr_b16 v[130:131], v212 offset:51712
	s_waitcnt lgkmcnt(14)
	v_mfma_f32_32x32x16_bf16 v[48:63], v[148:151], v[10:13], v[48:63]
	v_add_f32_e32 v80, v80, v100
	v_exp_f32_e32 v106, v106
	v_exp_f32_e32 v107, v107
	ds_read_b64_tr_b16 v[10:11], v212 offset:55296
	ds_read_b64_tr_b16 v[12:13], v212 offset:55808
	s_waitcnt lgkmcnt(14)
	v_mfma_f32_32x32x16_bf16 v[64:79], v[144:147], v[6:9], v[64:79]
	v_add_f32_e32 v80, v80, v101
	v_exp_f32_e32 v108, v108
	v_exp_f32_e32 v109, v109
	ds_read_b64_tr_b16 v[6:7], v212 offset:52224
	ds_read_b64_tr_b16 v[8:9], v212 offset:52736
	s_waitcnt lgkmcnt(14)
	v_mfma_f32_32x32x16_bf16 v[48:63], v[144:147], v[2:5], v[48:63]
	v_add_f32_e32 v80, v80, v102
	v_exp_f32_e32 v110, v110
	v_exp_f32_e32 v111, v111
	v_add_f32_e32 v136, 0, v80
	ds_read_b64_tr_b16 v[132:133], v212 offset:56320
	ds_read_b64_tr_b16 v[134:135], v212 offset:56832
	s_waitcnt lgkmcnt(14)
	v_mfma_f32_32x32x16_bf16 v[32:47], v[156:159], v[112:115], v[32:47]
	v_add_f32_e32 v2, v136, v103
	v_exp_f32_e32 v80, v14
	v_exp_f32_e32 v81, v15
	v_add_f32_e32 v2, v104, v2
	s_waitcnt lgkmcnt(12)
	v_mfma_f32_32x32x16_bf16 v[16:31], v[156:159], v[116:119], v[16:31]
	v_add_f32_e32 v2, v105, v2
	v_exp_f32_e32 v82, v82
	v_exp_f32_e32 v83, v83
	v_add_f32_e32 v2, v106, v2
	s_waitcnt lgkmcnt(10)
	v_mfma_f32_32x32x16_bf16 v[32:47], v[152:155], v[120:123], v[32:47]
	v_add_f32_e32 v2, v107, v2
	v_exp_f32_e32 v84, v84
	v_exp_f32_e32 v85, v85
	v_add_f32_e32 v2, v108, v2
	s_waitcnt lgkmcnt(8)
	v_mfma_f32_32x32x16_bf16 v[16:31], v[152:155], v[124:127], v[16:31]
	v_add_f32_e32 v2, v109, v2
	v_exp_f32_e32 v86, v86
	v_exp_f32_e32 v87, v87
	v_add_f32_e32 v2, v110, v2
	s_waitcnt lgkmcnt(6)
	v_mfma_f32_32x32x16_bf16 v[32:47], v[148:151], v[128:131], v[32:47]
	v_add_f32_e32 v2, v111, v2
	v_exp_f32_e32 v88, v88
	v_exp_f32_e32 v89, v89
	v_add_f32_e32 v2, v2, v80
	s_waitcnt lgkmcnt(4)
	v_mfma_f32_32x32x16_bf16 v[16:31], v[148:151], v[10:13], v[16:31]
	v_add_f32_e32 v2, v2, v81
	v_exp_f32_e32 v90, v90
	v_exp_f32_e32 v91, v91
	v_add_f32_e32 v2, v82, v2
	s_waitcnt lgkmcnt(2)
	v_mfma_f32_32x32x16_bf16 v[32:47], v[144:147], v[6:9], v[32:47]
	v_add_f32_e32 v2, v2, v83
	v_exp_f32_e32 v92, v92
	v_exp_f32_e32 v93, v93
	v_add_f32_e32 v2, v84, v2
	s_waitcnt lgkmcnt(0)
	v_mfma_f32_32x32x16_bf16 v[16:31], v[144:147], v[132:135], v[16:31]
	v_add_f32_e32 v2, v2, v85
	v_exp_f32_e32 v94, v94
	v_exp_f32_e32 v95, v95
	v_add_f32_e32 v3, v86, v2
	s_andn2_b64 vcc, exec, s[8:9]
	v_lshl_add_u32 v2, v239, 2, s56
	s_cbranch_vccnz .LBB0_1623
	s_waitcnt lgkmcnt(0)
	ds_read_b128 v[4:7], v2 offset:96
	ds_read_b128 v[8:11], v2 offset:64
	ds_read_b128 v[12:15], v2 offset:32
	ds_read_b128 v[112:115], v2
	s_waitcnt lgkmcnt(3)
	v_pk_mul_f32 v[78:79], v[78:79], v[6:7]
	s_waitcnt lgkmcnt(2)
	v_pk_mul_f32 v[74:75], v[74:75], v[10:11]
	s_waitcnt lgkmcnt(1)
	v_pk_mul_f32 v[70:71], v[70:71], v[14:15]
	s_waitcnt lgkmcnt(0)
	v_pk_mul_f32 v[66:67], v[66:67], v[114:115]
	v_pk_mul_f32 v[76:77], v[76:77], v[4:5]
	v_pk_mul_f32 v[72:73], v[72:73], v[8:9]
	v_pk_mul_f32 v[68:69], v[68:69], v[12:13]
	v_pk_mul_f32 v[64:65], v[64:65], v[112:113]
	v_pk_mul_f32 v[62:63], v[62:63], v[6:7]
	v_pk_mul_f32 v[58:59], v[58:59], v[10:11]
	v_pk_mul_f32 v[54:55], v[54:55], v[14:15]
	v_pk_mul_f32 v[50:51], v[50:51], v[114:115]
	v_pk_mul_f32 v[60:61], v[60:61], v[4:5]
	v_pk_mul_f32 v[56:57], v[56:57], v[8:9]
	v_pk_mul_f32 v[52:53], v[52:53], v[12:13]
	v_pk_mul_f32 v[48:49], v[48:49], v[112:113]
	v_pk_mul_f32 v[46:47], v[46:47], v[6:7]
	v_pk_mul_f32 v[42:43], v[42:43], v[10:11]
	v_pk_mul_f32 v[38:39], v[38:39], v[14:15]
	v_pk_mul_f32 v[34:35], v[34:35], v[114:115]
	v_pk_mul_f32 v[44:45], v[44:45], v[4:5]
	v_pk_mul_f32 v[40:41], v[40:41], v[8:9]
	v_pk_mul_f32 v[36:37], v[36:37], v[12:13]
	v_pk_mul_f32 v[32:33], v[32:33], v[112:113]
	v_pk_mul_f32 v[30:31], v[30:31], v[6:7]
	v_pk_mul_f32 v[26:27], v[26:27], v[10:11]
	v_pk_mul_f32 v[22:23], v[22:23], v[14:15]
	v_pk_mul_f32 v[18:19], v[18:19], v[114:115]
	v_pk_mul_f32 v[28:29], v[28:29], v[4:5]
	v_pk_mul_f32 v[24:25], v[24:25], v[8:9]
	v_pk_mul_f32 v[20:21], v[20:21], v[12:13]
	v_pk_mul_f32 v[16:17], v[16:17], v[112:113]

.LBB0_1632:
	s_waitcnt lgkmcnt(14)
	v_mfma_f32_32x32x16_bf16 v[64:79], v[156:159], v[220:223], v[64:79]
	v_exp_f32_e32 v96, v80
	v_exp_f32_e32 v97, v81
	ds_read_b64_tr_b16 v[112:113], v225 offset:49152
	ds_read_b64_tr_b16 v[114:115], v225 offset:49664
	s_waitcnt lgkmcnt(14)
	v_mfma_f32_32x32x16_bf16 v[48:63], v[156:159], v[204:207], v[48:63]
	v_exp_f32_e32 v98, v98
	v_exp_f32_e32 v99, v99
	ds_read_b64_tr_b16 v[116:117], v225 offset:53248
	ds_read_b64_tr_b16 v[118:119], v225 offset:53760
	v_add_u32_e32 v81, s62, v243
	ds_read_b128 v[204:207], v81
	ds_read_b128 v[200:203], v81 offset:512
	s_waitcnt lgkmcnt(14)
	v_mfma_f32_32x32x16_bf16 v[64:79], v[152:155], v[216:219], v[64:79]
	v_add_f32_e32 v80, v96, v97
	v_exp_f32_e32 v100, v100
	v_exp_f32_e32 v101, v101
	ds_read_b64_tr_b16 v[120:121], v225 offset:50176
	ds_read_b64_tr_b16 v[122:123], v225 offset:50688
	ds_read_b128 v[196:199], v81 offset:2048
	ds_read_b128 v[192:195], v81 offset:2560
	v_mfma_f32_32x32x16_bf16 v[48:63], v[152:155], v[212:215], v[48:63]
	v_add_f32_e32 v80, v80, v98
	v_exp_f32_e32 v102, v102
	v_exp_f32_e32 v103, v103
	ds_read_b64_tr_b16 v[124:125], v225 offset:54272
	ds_read_b64_tr_b16 v[126:127], v225 offset:54784
	ds_read_b128 v[188:191], v81 offset:4096
	ds_read_b128 v[184:187], v81 offset:4608
	s_waitcnt lgkmcnt(14)
	v_mfma_f32_32x32x16_bf16 v[64:79], v[148:151], v[208:211], v[64:79]
	v_add_f32_e32 v80, v80, v99
	v_exp_f32_e32 v104, v104
	v_exp_f32_e32 v105, v105
	ds_read_b64_tr_b16 v[128:129], v225 offset:51200
	ds_read_b64_tr_b16 v[130:131], v225 offset:51712
	ds_read_b128 v[180:183], v81 offset:6144
	ds_read_b128 v[176:179], v81 offset:6656
	v_mfma_f32_32x32x16_bf16 v[48:63], v[148:151], v[10:13], v[48:63]
	v_add_f32_e32 v80, v80, v100
	v_exp_f32_e32 v106, v106
	v_exp_f32_e32 v107, v107
	ds_read_b64_tr_b16 v[10:11], v225 offset:55296
	ds_read_b64_tr_b16 v[12:13], v225 offset:55808
	v_mfma_f32_32x32x16_bf16 v[64:79], v[144:147], v[6:9], v[64:79]
	v_add_f32_e32 v80, v80, v101
	v_exp_f32_e32 v108, v108
	v_exp_f32_e32 v109, v109
	ds_read_b64_tr_b16 v[6:7], v225 offset:52224
	ds_read_b64_tr_b16 v[8:9], v225 offset:52736
	v_mfma_f32_32x32x16_bf16 v[48:63], v[144:147], v[2:5], v[48:63]
	v_add_f32_e32 v80, v80, v102
	v_exp_f32_e32 v110, v110
	v_exp_f32_e32 v111, v111
	v_add_f32_e32 v132, 0, v80
	ds_read_b64_tr_b16 v[2:3], v225 offset:56320
	ds_read_b64_tr_b16 v[4:5], v225 offset:56832
	s_waitcnt lgkmcnt(14)
	v_mfma_f32_32x32x16_bf16 v[32:47], v[156:159], v[112:115], v[32:47]
	v_exp_f32_e32 v80, v14
	v_add_f32_e32 v14, v132, v103
	v_exp_f32_e32 v81, v15
	v_add_f32_e32 v14, v104, v14
	v_mfma_f32_32x32x16_bf16 v[16:31], v[156:159], v[116:119], v[16:31]
	v_add_f32_e32 v14, v105, v14
	v_exp_f32_e32 v82, v82
	v_exp_f32_e32 v83, v83
	v_add_f32_e32 v14, v106, v14
	v_mfma_f32_32x32x16_bf16 v[32:47], v[152:155], v[120:123], v[32:47]
	v_add_f32_e32 v14, v107, v14
	v_exp_f32_e32 v84, v84
	v_exp_f32_e32 v85, v85
	v_add_f32_e32 v14, v108, v14
	s_waitcnt lgkmcnt(12)
	v_mfma_f32_32x32x16_bf16 v[16:31], v[152:155], v[124:127], v[16:31]
	v_add_f32_e32 v14, v109, v14
	v_exp_f32_e32 v86, v86
	v_exp_f32_e32 v87, v87
	v_add_f32_e32 v14, v110, v14
	s_waitcnt lgkmcnt(8)
	v_mfma_f32_32x32x16_bf16 v[32:47], v[148:151], v[128:131], v[32:47]
	v_add_f32_e32 v14, v111, v14
	v_exp_f32_e32 v88, v88
	v_exp_f32_e32 v89, v89
	v_add_f32_e32 v14, v14, v80
	s_waitcnt lgkmcnt(4)
	v_mfma_f32_32x32x16_bf16 v[16:31], v[148:151], v[10:13], v[16:31]
	v_add_f32_e32 v14, v14, v81
	v_exp_f32_e32 v90, v90
	v_exp_f32_e32 v91, v91
	v_add_f32_e32 v14, v82, v14
	s_waitcnt lgkmcnt(2)
	v_mfma_f32_32x32x16_bf16 v[32:47], v[144:147], v[6:9], v[32:47]
	v_add_f32_e32 v10, v14, v83
	v_exp_f32_e32 v92, v92
	v_exp_f32_e32 v93, v93
	v_add_f32_e32 v10, v84, v10
	s_waitcnt lgkmcnt(0)
	v_mfma_f32_32x32x16_bf16 v[16:31], v[144:147], v[2:5], v[16:31]
	v_add_f32_e32 v6, v10, v85
	v_exp_f32_e32 v94, v94
	v_exp_f32_e32 v95, v95
	v_add_f32_e32 v14, v86, v6
	s_mov_b64 s[26:27], -1
	s_and_b64 vcc, exec, s[24:25]
	s_cbranch_vccnz .LBB0_1657
	s_andn2_b64 vcc, exec, s[26:27]
	s_cbranch_vccz .LBB0_1662

.LBB0_1643:
	s_waitcnt lgkmcnt(14)
	v_mfma_f32_32x32x16_bf16 v[64:79], v[156:159], v[224:227], v[64:79]
	v_exp_f32_e32 v96, v80
	v_exp_f32_e32 v97, v81
	ds_read_b64_tr_b16 v[112:113], v248 offset:49152
	ds_read_b64_tr_b16 v[114:115], v248 offset:49664
	s_waitcnt lgkmcnt(14)
	v_mfma_f32_32x32x16_bf16 v[48:63], v[156:159], v[220:223], v[48:63]
	v_mov_b32_e32 v80, v96
	v_exp_f32_e32 v98, v98
	v_exp_f32_e32 v99, v99
	v_add_f32_e32 v81, 0, v80
	ds_read_b64_tr_b16 v[116:117], v248 offset:53248
	ds_read_b64_tr_b16 v[118:119], v248 offset:53760
	v_cndmask_b32_e64 v80, 0, 1, s[30:31]
	v_cmp_ne_u32_e64 s[10:11], 1, v80
	s_andn2_b64 vcc, exec, s[30:31]
	v_add_u32_e32 v80, s61, v243
	s_cbranch_vccnz .LBB0_1645
	ds_read_b128 v[204:207], v80
	ds_read_b128 v[200:203], v80 offset:512
.LBB0_1645:
	s_waitcnt lgkmcnt(14)
	v_mfma_f32_32x32x16_bf16 v[64:79], v[152:155], v[216:219], v[64:79]
	v_add_f32_e32 v81, v81, v97
	v_exp_f32_e32 v100, v100
	v_exp_f32_e32 v101, v101
	ds_read_b64_tr_b16 v[120:121], v248 offset:50176
	ds_read_b64_tr_b16 v[122:123], v248 offset:50688
	s_and_b64 vcc, exec, s[10:11]
	s_cbranch_vccnz .LBB0_1647
	ds_read_b128 v[196:199], v80 offset:2048
	ds_read_b128 v[192:195], v80 offset:2560
.LBB0_1647:
	s_waitcnt lgkmcnt(14)
	v_mfma_f32_32x32x16_bf16 v[48:63], v[152:155], v[212:215], v[48:63]
	v_add_f32_e32 v81, v81, v98
	v_exp_f32_e32 v102, v102
	v_exp_f32_e32 v103, v103
	ds_read_b64_tr_b16 v[124:125], v248 offset:54272
	ds_read_b64_tr_b16 v[126:127], v248 offset:54784
	s_and_b64 vcc, exec, s[10:11]
	s_cbranch_vccnz .LBB0_1649
	ds_read_b128 v[188:191], v80 offset:4096
	ds_read_b128 v[184:187], v80 offset:4608
.LBB0_1649:
	s_waitcnt lgkmcnt(14)
	v_mfma_f32_32x32x16_bf16 v[64:79], v[148:151], v[208:211], v[64:79]
	v_add_f32_e32 v81, v81, v99
	v_exp_f32_e32 v104, v104
	v_exp_f32_e32 v105, v105
	ds_read_b64_tr_b16 v[128:129], v248 offset:51200
	ds_read_b64_tr_b16 v[130:131], v248 offset:51712
	s_and_b64 vcc, exec, s[10:11]
	s_cbranch_vccnz .LBB0_1651
	ds_read_b128 v[180:183], v80 offset:6144
	ds_read_b128 v[176:179], v80 offset:6656
.LBB0_1651:
	s_waitcnt lgkmcnt(14)
	v_mfma_f32_32x32x16_bf16 v[48:63], v[148:151], v[10:13], v[48:63]
	v_add_f32_e32 v80, v81, v100
	v_exp_f32_e32 v106, v106
	v_exp_f32_e32 v107, v107
	ds_read_b64_tr_b16 v[10:11], v248 offset:55296
	ds_read_b64_tr_b16 v[12:13], v248 offset:55808
	s_waitcnt lgkmcnt(14)
	v_mfma_f32_32x32x16_bf16 v[64:79], v[144:147], v[6:9], v[64:79]
	v_add_f32_e32 v80, v80, v101
	v_exp_f32_e32 v108, v108
	v_exp_f32_e32 v109, v109
	ds_read_b64_tr_b16 v[6:7], v248 offset:52224
	ds_read_b64_tr_b16 v[8:9], v248 offset:52736
	s_waitcnt lgkmcnt(14)
	v_mfma_f32_32x32x16_bf16 v[48:63], v[144:147], v[2:5], v[48:63]
	v_add_f32_e32 v80, v80, v102
	v_exp_f32_e32 v110, v110
	v_exp_f32_e32 v111, v111
	v_add_f32_e32 v136, 0, v80
	ds_read_b64_tr_b16 v[132:133], v248 offset:56320
	ds_read_b64_tr_b16 v[134:135], v248 offset:56832
	s_waitcnt lgkmcnt(14)
	v_mfma_f32_32x32x16_bf16 v[32:47], v[156:159], v[112:115], v[32:47]
	v_add_f32_e32 v2, v136, v103
	v_exp_f32_e32 v80, v14
	v_exp_f32_e32 v81, v15
	v_add_f32_e32 v2, v104, v2
	s_waitcnt lgkmcnt(12)
	v_mfma_f32_32x32x16_bf16 v[16:31], v[156:159], v[116:119], v[16:31]
	v_add_f32_e32 v2, v105, v2
	v_exp_f32_e32 v82, v82
	v_exp_f32_e32 v83, v83
	v_add_f32_e32 v2, v106, v2
	s_waitcnt lgkmcnt(10)
	v_mfma_f32_32x32x16_bf16 v[32:47], v[152:155], v[120:123], v[32:47]
	v_add_f32_e32 v2, v107, v2
	v_exp_f32_e32 v84, v84
	v_exp_f32_e32 v85, v85
	v_add_f32_e32 v2, v108, v2
	s_waitcnt lgkmcnt(8)
	v_mfma_f32_32x32x16_bf16 v[16:31], v[152:155], v[124:127], v[16:31]
	v_add_f32_e32 v2, v109, v2
	v_exp_f32_e32 v86, v86
	v_exp_f32_e32 v87, v87
	v_add_f32_e32 v2, v110, v2
	s_waitcnt lgkmcnt(6)
	v_mfma_f32_32x32x16_bf16 v[32:47], v[148:151], v[128:131], v[32:47]
	v_add_f32_e32 v2, v111, v2
	v_exp_f32_e32 v88, v88
	v_exp_f32_e32 v89, v89
	v_add_f32_e32 v2, v2, v80
	s_waitcnt lgkmcnt(4)
	v_mfma_f32_32x32x16_bf16 v[16:31], v[148:151], v[10:13], v[16:31]
	v_add_f32_e32 v2, v2, v81
	v_exp_f32_e32 v90, v90
	v_exp_f32_e32 v91, v91
	v_add_f32_e32 v2, v82, v2
	s_waitcnt lgkmcnt(2)
	v_mfma_f32_32x32x16_bf16 v[32:47], v[144:147], v[6:9], v[32:47]
	v_add_f32_e32 v2, v2, v83
	v_exp_f32_e32 v92, v92
	v_exp_f32_e32 v93, v93
	v_add_f32_e32 v2, v84, v2
	s_waitcnt lgkmcnt(0)
	v_mfma_f32_32x32x16_bf16 v[16:31], v[144:147], v[132:135], v[16:31]
	v_add_f32_e32 v2, v2, v85
	v_exp_f32_e32 v94, v94
	v_exp_f32_e32 v95, v95
	v_add_f32_e32 v2, v86, v2
	s_mov_b64 s[10:11], -1
	s_and_b64 vcc, exec, s[26:27]
	s_cbranch_vccnz .LBB0_1663
	s_andn2_b64 vcc, exec, s[10:11]
	s_cbranch_vccz .LBB0_1668
